# attention 64-key rounds (all unrolled tile copies): V fragments read with ds_read_b64 straight into MFMA operand order, 180 v_mov shuffles removed; VALU-to-MFMA wait states re-derived
# baseline (speedup 1.0000x reference)
; template <bool SWA>
; DI void attn_phase(const Ctx& a, LAS unsigned char* lds) {
;     ...
;                 for (int jt = 0; jt < 4; ++jt) {
;                     const int row = 16 * jt + fr; const int sw = (row >> 1) & 7;
;                     const bf16x8 k0 = *(const LAS bf16x8*)(lds + AT_K + buf * 8192 + row * 128 + ((fq ^ sw) << 4));
;                     const bf16x8 k1 = *(const LAS bf16x8*)(lds + AT_K + buf * 8192 + row * 128 + (((4 + fq) ^ sw) << 4));
;                     f32x4 acc = (f32x4){0.f, 0.f, 0.f, 0.f}; acc = MFMA16(k0, qf[0], acc); acc = MFMA16(k1, qf[1], acc); sc[jt] = acc;
;                 }
;                 float sv[16]; bool ok[16];
; #pragma unroll
;                 for (int jt = 0; jt < 4; ++jt)
; #pragma unroll
;                     for (int rr = 0; rr < 4; ++rr) {
;                         bool valid = true;
;                         if (SWA && local) { const int dd = tkey0 + 16 * jt + 4 * fq + rr - (tq0 + fr); valid = (dd <= 128) && (dd >= -128); }
;                         sv[jt * 4 + rr] = valid ? sc[jt][rr] : -1e30f; ok[jt * 4 + rr] = valid;
;                     }
;                 float cmax = sv[0];
; #pragma unroll
;                 for (int e = 1; e < 16; ++e) cmax = fmaxf(cmax, sv[e]);
;                 cmax = fmaxf(cmax, shx(cmax, 16, lane)); cmax = fmaxf(cmax, shx(cmax, 32, lane));
;                 const float m_new = fmaxf(m_run, cmax);
;                 const float alpha = __builtin_amdgcn_exp2f((m_run - m_new) * LOG2E);
;                 float p[16], psum = 0.f;
; #pragma unroll
;                 for (int e = 0; e < 16; ++e) { p[e] = ok[e] ? __builtin_amdgcn_exp2f((sv[e] - m_new) * LOG2E) : 0.f; psum += p[e]; }
;                 l_run = l_run * alpha + psum; m_run = m_new;
;                 u32x4 pw0, pw1; pw0.x = pk2(p[0], p[1]); pw0.y = pk2(p[2], p[3]); pw0.z = pk2(p[4], p[5]); pw0.w = pk2(p[6], p[7]);
;                 pw1.x = pk2(p[8], p[9]); pw1.y = pk2(p[10], p[11]); pw1.z = pk2(p[12], p[13]); pw1.w = pk2(p[14], p[15]);
;                 const bf16x8 pf0 = __builtin_bit_cast(bf16x8, pw0), pf1 = __builtin_bit_cast(bf16x8, pw1);
;                 if (__builtin_amdgcn_ballot_w64(alpha != 1.f) != 0ull) {
; #pragma unroll
;                     for (int dt = 0; dt < 4; ++dt) o[dt] = o[dt] * alpha;
;                 }
;                 const int kc = (fq >> 1), kb8 = (fq & 1) * 8;
; #pragma unroll
.LBB0_78:
	v_add_u32_e32 v79, v65, v66
	v_add_u32_e32 v80, v65, v67
	ds_read_b128 v[0:3], v79
	ds_read_b128 v[4:7], v79 offset:2048
	ds_read_b128 v[8:11], v80
	ds_read_b128 v[20:23], v80 offset:2048
	s_waitcnt lgkmcnt(0)
	v_mfma_f32_16x16x32_bf16 v[0:3], v[0:3], v[12:15], 0
	v_add_u32_e32 v77, v74, v70
	v_add_u32_e32 v78, v74, v71
	v_add_u32_e32 v76, v74, v73
	v_mfma_f32_16x16x32_bf16 v[0:3], v[8:11], v[16:19], v[0:3]
	ds_read_b128 v[8:11], v79 offset:4096
	v_mfma_f32_16x16x32_bf16 v[4:7], v[4:7], v[12:15], 0
	s_nop 5
	v_max_f32_e32 v34, v1, v1
	v_max_f32_e32 v35, v0, v0
	v_mfma_f32_16x16x32_bf16 v[4:7], v[20:23], v[16:19], v[4:7]
	ds_read_b128 v[20:23], v80 offset:4096
	ds_read_b128 v[26:29], v79 offset:6144
	ds_read_b128 v[30:33], v80 offset:6144
	ds_read_b64 v[122:123], v76 offset:24576
	ds_read_b64 v[130:131], v76 offset:26624
	s_waitcnt lgkmcnt(0)
	v_mfma_f32_16x16x32_bf16 v[8:11], v[8:11], v[12:15], 0
	v_mfma_f32_16x16x32_bf16 v[8:11], v[20:23], v[16:19], v[8:11]
	v_max_f32_e32 v20, v35, v34
	v_max3_f32 v20, v20, v2, v3
	v_max3_f32 v34, v20, v4, v5
	v_mfma_f32_16x16x32_bf16 v[20:23], v[26:29], v[12:15], 0
	v_max3_f32 v26, v34, v6, v7
	s_nop 2
	v_max3_f32 v26, v26, v8, v9
	v_max3_f32 v26, v26, v10, v11
	v_mfma_f32_16x16x32_bf16 v[20:23], v[30:33], v[16:19], v[20:23]
	s_nop 6
	v_max3_f32 v26, v26, v20, v21
	v_max3_f32 v26, v26, v22, v23
	ds_bpermute_b32 v27, v68, v26
	s_waitcnt lgkmcnt(0)
	v_max_f32_e32 v27, v27, v27
	v_max_f32_e32 v26, v26, v27
	ds_bpermute_b32 v27, v69, v26
	s_waitcnt lgkmcnt(0)
	v_max3_f32 v60, v25, v26, v27
	v_sub_f32_e32 v0, v0, v60
	v_sub_f32_e32 v25, v25, v60
	v_mul_f32_e32 v0, 0x3fb8aa3b, v0
	v_mul_f32_e32 v49, 0x3fb8aa3b, v25
	v_exp_f32_e32 v25, v0
	v_sub_f32_e32 v0, v3, v60
	v_mul_f32_e32 v0, 0x3fb8aa3b, v0
	v_exp_f32_e32 v28, v0
	v_sub_f32_e32 v0, v4, v60
	v_mul_f32_e32 v0, 0x3fb8aa3b, v0
	v_exp_f32_e32 v29, v0
	v_sub_f32_e32 v0, v5, v60
	v_mul_f32_e32 v0, 0x3fb8aa3b, v0
	v_exp_f32_e32 v30, v0
	v_sub_f32_e32 v0, v6, v60
	v_mul_f32_e32 v0, 0x3fb8aa3b, v0
	v_exp_f32_e32 v31, v0
	v_sub_f32_e32 v0, v7, v60
	v_mul_f32_e32 v0, 0x3fb8aa3b, v0
	v_exp_f32_e32 v32, v0
	v_sub_f32_e32 v0, v8, v60
	v_mul_f32_e32 v0, 0x3fb8aa3b, v0
	v_exp_f32_e32 v33, v0
	v_sub_f32_e32 v0, v9, v60
	v_exp_f32_e32 v84, v49
	v_mul_f32_e32 v0, 0x3fb8aa3b, v0
	v_exp_f32_e32 v34, v0
	v_sub_f32_e32 v0, v10, v60
	v_mul_f32_e32 v0, 0x3fb8aa3b, v0
	v_exp_f32_e32 v35, v0
	v_sub_f32_e32 v0, v11, v60
	v_cmp_neq_f32_e32 vcc, 1.0, v84
	v_mul_f32_e32 v0, 0x3fb8aa3b, v0
	s_cmp_lg_u64 vcc, 0
	v_exp_f32_e32 v36, v0
	v_sub_f32_e32 v0, v20, v60
	v_mul_f32_e32 v4, 0, v84
	s_cselect_b64 vcc, -1, 0
	v_mul_f32_e32 v0, 0x3fb8aa3b, v0
	v_cndmask_b32_e32 v90, 0, v4, vcc
	ds_read_b64 v[116:117], v77 offset:24576
	ds_read_b64 v[124:125], v77 offset:26624
	ds_read_b64 v[118:119], v78 offset:24576
	ds_read_b64 v[126:127], v78 offset:26624
	v_exp_f32_e32 v37, v0
	v_sub_f32_e32 v0, v21, v60
	v_mul_f32_e32 v0, 0x3fb8aa3b, v0
	v_sub_f32_e32 v1, v1, v60
	v_sub_f32_e32 v2, v2, v60
	v_exp_f32_e32 v38, v0
	v_sub_f32_e32 v0, v22, v60
	v_add_u32_e32 v49, v74, v72
	v_mul_f32_e32 v1, 0x3fb8aa3b, v1
	v_mul_f32_e32 v2, 0x3fb8aa3b, v2
	v_mul_f32_e32 v0, 0x3fb8aa3b, v0
	ds_read_b64 v[120:121], v49 offset:24576
	ds_read_b64 v[128:129], v49 offset:26624
	v_exp_f32_e32 v26, v1
	v_exp_f32_e32 v27, v2
	v_exp_f32_e32 v39, v0
	v_sub_f32_e32 v0, v23, v60
	s_waitcnt lgkmcnt(0)
	v_mul_f32_e32 v0, 0x3fb8aa3b, v0
	v_exp_f32_e32 v83, v0
	v_cvt_pk_bf16_f32 v0, v25, v26
	v_cvt_pk_bf16_f32 v1, v27, v28
	v_cvt_pk_bf16_f32 v2, v29, v30
	v_cvt_pk_bf16_f32 v3, v31, v32
	v_mov_b32_e32 v91, v90
	v_mov_b32_e32 v92, v90
	v_mov_b32_e32 v93, v90
	s_nop 1
	v_mfma_f32_16x16x32_bf16 v[20:23], v[116:119], v[0:3], v[90:93]
	v_cvt_pk_bf16_f32 v86, v33, v34
	v_cvt_pk_bf16_f32 v87, v35, v36
	v_cvt_pk_bf16_f32 v88, v37, v38
	v_cvt_pk_bf16_f32 v89, v39, v83
	s_nop 1
	v_mfma_f32_16x16x32_bf16 v[20:23], v[120:123], v[86:89], v[20:23]
	ds_read_b64 v[132:133], v77 offset:28672
	ds_read_b64 v[136:137], v77 offset:30720
	ds_read_b64 v[134:135], v78 offset:28672
	ds_read_b64 v[138:139], v78 offset:30720
	s_andn2_b64 vcc, exec, s[30:31]
	s_mov_b64 s[30:31], -1
	v_mfma_f32_16x16x32_bf16 v[4:7], v[124:127], v[0:3], v[90:93]
	v_mfma_f32_16x16x32_bf16 v[8:11], v[128:131], v[86:89], v[4:7]
	ds_read_b64 v[140:141], v49 offset:28672
	ds_read_b64 v[160:161], v49 offset:30720
	ds_read_b64 v[142:143], v76 offset:28672
	ds_read_b64 v[162:163], v76 offset:30720
	s_waitcnt lgkmcnt(0)
	s_nop 2
	v_mfma_f32_16x16x32_bf16 v[4:7], v[132:135], v[0:3], v[90:93]
	v_mfma_f32_16x16x32_bf16 v[0:3], v[136:139], v[0:3], v[90:93]
	v_mfma_f32_16x16x32_bf16 v[4:7], v[140:143], v[86:89], v[4:7]
	v_mfma_f32_16x16x32_bf16 v[0:3], v[160:163], v[86:89], v[0:3]
	s_cbranch_vccnz .LBB0_80
	s_waitcnt vmcnt(0)
	s_mov_b64 s[30:31], 0

; #define LAS __attribute__((address_space(3)))
; #define MFMA16(a, b, c) __builtin_amdgcn_mfma_f32_16x16x32_bf16((a), (b), (c), 0, 0, 0)
; template <bool SWA>
; DI void attn_phase(const Ctx& a, LAS unsigned char* lds) {
;     ...
;                 const int kc = (fq >> 1), kb8 = (fq & 1) * 8;
; #pragma unroll
;                 for (int dt = 0; dt < 4; ++dt) {
;                     const int d = 16 * dt + fr, sw = (d >> 1) & 7; const int vb = AT_V + buf * 8192 + d * 128 + kb8;
;                     const s16x4 v0 = *(const LAS s16x4*)(lds + vb + ((kc ^ sw) << 4)), v1 = *(const LAS s16x4*)(lds + vb + (((kc + 2) ^ sw) << 4));
;                     const s16x4 v2 = *(const LAS s16x4*)(lds + vb + (((kc + 4) ^ sw) << 4)), v3 = *(const LAS s16x4*)(lds + vb + (((kc + 6) ^ sw) << 4));
;                     o[dt] = MFMA16(__builtin_shufflevector(v0, v1, 0, 1, 2, 3, 4, 5, 6, 7), pf0, o[dt]);
;                     o[dt] = MFMA16(__builtin_shufflevector(v2, v3, 0, 1, 2, 3, 4, 5, 6, 7), pf1, o[dt]);
;                 }
.LBB0_87:
	ds_read_b64 v[116:117], v77 offset:32768
	ds_read_b64 v[120:121], v77 offset:34816
	s_mov_b32 s98, 0x3fb8aa3b
	v_mul_f32_e32 v190, 0xbfb8aa3b, v85
	v_fma_f32 v24, v24, s98, v190
	v_fma_f32 v25, v25, s98, v190
	v_fma_f32 v26, v26, s98, v190
	v_fma_f32 v27, v27, s98, v190
	v_fma_f32 v28, v28, s98, v190
	v_fma_f32 v29, v29, s98, v190
	v_fma_f32 v30, v30, s98, v190
	v_fma_f32 v31, v31, s98, v190
	v_exp_f32_e32 v24, v24
	v_exp_f32_e32 v25, v25
	v_exp_f32_e32 v26, v26
	v_exp_f32_e32 v27, v27
	v_exp_f32_e32 v28, v28
	v_exp_f32_e32 v29, v29
	v_exp_f32_e32 v30, v30
	v_exp_f32_e32 v31, v31
	s_waitcnt lgkmcnt(0)
	ds_read_b64 v[118:119], v78 offset:32768
	ds_read_b64 v[122:123], v78 offset:34816
	ds_read_b64 v[124:125], v49 offset:32768
	ds_read_b64 v[128:129], v49 offset:34816
	ds_read_b64 v[126:127], v76 offset:32768
	ds_read_b64 v[130:131], v76 offset:34816
	v_cvt_pk_bf16_f32 v86, v24, v25
	v_cvt_pk_bf16_f32 v87, v26, v27
	v_cvt_pk_bf16_f32 v88, v28, v29
	v_cvt_pk_bf16_f32 v89, v30, v31
	v_fma_f32 v32, v32, s98, v190
	v_fma_f32 v33, v33, s98, v190
	s_waitcnt lgkmcnt(0)
	v_mfma_f32_16x16x32_bf16 v[20:23], v[116:119], v[86:89], v[20:23]
	v_fma_f32 v34, v34, s98, v190
	v_fma_f32 v35, v35, s98, v190
	v_fma_f32 v36, v36, s98, v190
	v_fma_f32 v37, v37, s98, v190
	v_fma_f32 v38, v38, s98, v190
	v_fma_f32 v39, v39, s98, v190
	v_exp_f32_e32 v32, v32
	v_exp_f32_e32 v33, v33
	v_exp_f32_e32 v34, v34
	v_exp_f32_e32 v35, v35
	v_exp_f32_e32 v36, v36
	v_exp_f32_e32 v37, v37
	v_exp_f32_e32 v38, v38
	v_exp_f32_e32 v39, v39
	v_mfma_f32_16x16x32_bf16 v[8:11], v[120:123], v[86:89], v[8:11]
	ds_read_b64 v[132:133], v77 offset:36864
	ds_read_b64 v[136:137], v77 offset:38912
	ds_read_b64 v[134:135], v78 offset:36864
	ds_read_b64 v[138:139], v78 offset:38912
	v_cvt_pk_bf16_f32 v94, v32, v33
	v_cvt_pk_bf16_f32 v95, v34, v35
	v_cvt_pk_bf16_f32 v96, v36, v37
	v_cvt_pk_bf16_f32 v97, v38, v39
	s_waitcnt lgkmcnt(0)
	s_nop 0
	v_mfma_f32_16x16x32_bf16 v[20:23], v[124:127], v[94:97], v[20:23]
	v_mfma_f32_16x16x32_bf16 v[8:11], v[128:131], v[94:97], v[8:11]
	ds_read_b64 v[140:141], v49 offset:36864
	ds_read_b64 v[160:161], v49 offset:38912
	ds_read_b64 v[142:143], v76 offset:36864
	ds_read_b64 v[162:163], v76 offset:38912
	s_andn2_b64 vcc, exec, s[30:31]
	v_mfma_f32_16x16x32_bf16 v[4:7], v[132:135], v[86:89], v[4:7]
	s_waitcnt lgkmcnt(0)
	v_mfma_f32_16x16x32_bf16 v[0:3], v[136:139], v[86:89], v[0:3]
	s_mov_b64 s[30:31], -1
	v_mfma_f32_16x16x32_bf16 v[4:7], v[140:143], v[94:97], v[4:7]
	v_mfma_f32_16x16x32_bf16 v[0:3], v[160:163], v[94:97], v[0:3]
	s_cbranch_vccnz .LBB0_89
	s_waitcnt vmcnt(0)
	s_mov_b64 s[30:31], 0

; #define LAS __attribute__((address_space(3)))
; #define MFMA16(a, b, c) __builtin_amdgcn_mfma_f32_16x16x32_bf16((a), (b), (c), 0, 0, 0)
; template <bool SWA>
; DI void attn_phase(const Ctx& a, LAS unsigned char* lds) {
;     ...
;                 const int kc = (fq >> 1), kb8 = (fq & 1) * 8;
; #pragma unroll
;                 for (int dt = 0; dt < 4; ++dt) {
;                     const int d = 16 * dt + fr, sw = (d >> 1) & 7; const int vb = AT_V + buf * 8192 + d * 128 + kb8;
;                     const s16x4 v0 = *(const LAS s16x4*)(lds + vb + ((kc ^ sw) << 4)), v1 = *(const LAS s16x4*)(lds + vb + (((kc + 2) ^ sw) << 4));
;                     const s16x4 v2 = *(const LAS s16x4*)(lds + vb + (((kc + 4) ^ sw) << 4)), v3 = *(const LAS s16x4*)(lds + vb + (((kc + 6) ^ sw) << 4));
;                     o[dt] = MFMA16(__builtin_shufflevector(v0, v1, 0, 1, 2, 3, 4, 5, 6, 7), pf0, o[dt]);
;                     o[dt] = MFMA16(__builtin_shufflevector(v2, v3, 0, 1, 2, 3, 4, 5, 6, 7), pf1, o[dt]);
;                 }
.LBB0_96:
	ds_read_b64 v[116:117], v77 offset:40960
	ds_read_b64 v[120:121], v77 offset:43008
	s_mov_b32 s98, 0x3fb8aa3b
	v_mul_f32_e32 v190, 0xbfb8aa3b, v82
	v_fma_f32 v24, v24, s98, v190
	v_fma_f32 v25, v25, s98, v190
	v_fma_f32 v26, v26, s98, v190
	v_fma_f32 v27, v27, s98, v190
	v_fma_f32 v28, v28, s98, v190
	v_fma_f32 v29, v29, s98, v190
	v_fma_f32 v30, v30, s98, v190
	v_fma_f32 v31, v31, s98, v190
	v_exp_f32_e32 v24, v24
	v_exp_f32_e32 v25, v25
	v_exp_f32_e32 v26, v26
	v_exp_f32_e32 v27, v27
	v_exp_f32_e32 v28, v28
	v_exp_f32_e32 v29, v29
	v_exp_f32_e32 v30, v30
	v_exp_f32_e32 v31, v31
	s_waitcnt lgkmcnt(0)
	ds_read_b64 v[118:119], v78 offset:40960
	ds_read_b64 v[122:123], v78 offset:43008
	ds_read_b64 v[124:125], v49 offset:40960
	ds_read_b64 v[128:129], v49 offset:43008
	ds_read_b64 v[126:127], v76 offset:40960
	ds_read_b64 v[130:131], v76 offset:43008
	v_cvt_pk_bf16_f32 v86, v24, v25
	v_cvt_pk_bf16_f32 v87, v26, v27
	v_cvt_pk_bf16_f32 v88, v28, v29
	v_cvt_pk_bf16_f32 v89, v30, v31
	v_fma_f32 v32, v32, s98, v190
	v_fma_f32 v33, v33, s98, v190
	s_waitcnt lgkmcnt(0)
	v_mfma_f32_16x16x32_bf16 v[20:23], v[116:119], v[86:89], v[20:23]
	v_fma_f32 v34, v34, s98, v190
	v_fma_f32 v35, v35, s98, v190
	v_fma_f32 v36, v36, s98, v190
	v_fma_f32 v37, v37, s98, v190
	v_fma_f32 v38, v38, s98, v190
	v_fma_f32 v39, v39, s98, v190
	v_exp_f32_e32 v32, v32
	v_exp_f32_e32 v33, v33
	v_exp_f32_e32 v34, v34
	v_exp_f32_e32 v35, v35
	v_exp_f32_e32 v36, v36
	v_exp_f32_e32 v37, v37
	v_exp_f32_e32 v38, v38
	v_exp_f32_e32 v39, v39
	v_mfma_f32_16x16x32_bf16 v[8:11], v[120:123], v[86:89], v[8:11]
	ds_read_b64 v[132:133], v77 offset:45056
	ds_read_b64 v[136:137], v77 offset:47104
	ds_read_b64 v[134:135], v78 offset:45056
	ds_read_b64 v[138:139], v78 offset:47104
	v_cvt_pk_bf16_f32 v94, v32, v33
	v_cvt_pk_bf16_f32 v95, v34, v35
	v_cvt_pk_bf16_f32 v96, v36, v37
	v_cvt_pk_bf16_f32 v97, v38, v39
	s_waitcnt lgkmcnt(0)
	s_nop 0
	v_mfma_f32_16x16x32_bf16 v[20:23], v[124:127], v[94:97], v[20:23]
	v_mfma_f32_16x16x32_bf16 v[8:11], v[128:131], v[94:97], v[8:11]
	ds_read_b64 v[140:141], v49 offset:45056
	ds_read_b64 v[160:161], v49 offset:47104
	ds_read_b64 v[142:143], v76 offset:45056
	ds_read_b64 v[162:163], v76 offset:47104
	s_andn2_b64 vcc, exec, s[30:31]
	v_mfma_f32_16x16x32_bf16 v[4:7], v[132:135], v[86:89], v[4:7]
	s_waitcnt lgkmcnt(0)
	v_mfma_f32_16x16x32_bf16 v[0:3], v[136:139], v[86:89], v[0:3]
	s_mov_b64 s[30:31], -1
	v_mfma_f32_16x16x32_bf16 v[4:7], v[140:143], v[94:97], v[4:7]
	v_mfma_f32_16x16x32_bf16 v[0:3], v[160:163], v[94:97], v[0:3]
	s_cbranch_vccnz .LBB0_98
	s_waitcnt vmcnt(0)
	s_mov_b64 s[30:31], 0

; #define LAS __attribute__((address_space(3)))
; #define MFMA16(a, b, c) __builtin_amdgcn_mfma_f32_16x16x32_bf16((a), (b), (c), 0, 0, 0)
; template <bool SWA>
; DI void attn_phase(const Ctx& a, LAS unsigned char* lds) {
;     ...
;                 const int kc = (fq >> 1), kb8 = (fq & 1) * 8;
; #pragma unroll
;                 for (int dt = 0; dt < 4; ++dt) {
;                     const int d = 16 * dt + fr, sw = (d >> 1) & 7; const int vb = AT_V + buf * 8192 + d * 128 + kb8;
;                     const s16x4 v0 = *(const LAS s16x4*)(lds + vb + ((kc ^ sw) << 4)), v1 = *(const LAS s16x4*)(lds + vb + (((kc + 2) ^ sw) << 4));
;                     const s16x4 v2 = *(const LAS s16x4*)(lds + vb + (((kc + 4) ^ sw) << 4)), v3 = *(const LAS s16x4*)(lds + vb + (((kc + 6) ^ sw) << 4));
;                     o[dt] = MFMA16(__builtin_shufflevector(v0, v1, 0, 1, 2, 3, 4, 5, 6, 7), pf0, o[dt]);
;                     o[dt] = MFMA16(__builtin_shufflevector(v2, v3, 0, 1, 2, 3, 4, 5, 6, 7), pf1, o[dt]);
;                 }
.LBB0_105:
	ds_read_b64 v[116:117], v77 offset:24576
	ds_read_b64 v[120:121], v77 offset:26624
	s_mov_b32 s98, 0x3fb8aa3b
	v_mul_f32_e32 v190, 0xbfb8aa3b, v79
	v_fma_f32 v24, v24, s98, v190
	v_fma_f32 v25, v25, s98, v190
	v_fma_f32 v26, v26, s98, v190
	v_fma_f32 v27, v27, s98, v190
	v_fma_f32 v28, v28, s98, v190
	v_fma_f32 v29, v29, s98, v190
	v_fma_f32 v30, v30, s98, v190
	v_fma_f32 v31, v31, s98, v190
	v_exp_f32_e32 v24, v24
	v_exp_f32_e32 v25, v25
	v_exp_f32_e32 v26, v26
	v_exp_f32_e32 v27, v27
	v_exp_f32_e32 v28, v28
	v_exp_f32_e32 v29, v29
	v_exp_f32_e32 v30, v30
	v_exp_f32_e32 v31, v31
	s_waitcnt lgkmcnt(0)
	ds_read_b64 v[118:119], v78 offset:24576
	ds_read_b64 v[122:123], v78 offset:26624
	ds_read_b64 v[124:125], v49 offset:24576
	ds_read_b64 v[128:129], v49 offset:26624
	ds_read_b64 v[126:127], v76 offset:24576
	ds_read_b64 v[130:131], v76 offset:26624
	v_cvt_pk_bf16_f32 v82, v24, v25
	v_cvt_pk_bf16_f32 v83, v26, v27
	v_cvt_pk_bf16_f32 v84, v28, v29
	v_cvt_pk_bf16_f32 v85, v30, v31
	v_fma_f32 v32, v32, s98, v190
	v_fma_f32 v33, v33, s98, v190
	s_waitcnt lgkmcnt(0)
	v_mfma_f32_16x16x32_bf16 v[20:23], v[116:119], v[82:85], v[20:23]
	v_fma_f32 v34, v34, s98, v190
	v_fma_f32 v35, v35, s98, v190
	v_fma_f32 v36, v36, s98, v190
	v_fma_f32 v37, v37, s98, v190
	v_fma_f32 v38, v38, s98, v190
	v_fma_f32 v39, v39, s98, v190
	v_exp_f32_e32 v32, v32
	v_exp_f32_e32 v33, v33
	v_exp_f32_e32 v34, v34
	v_exp_f32_e32 v35, v35
	v_exp_f32_e32 v36, v36
	v_exp_f32_e32 v37, v37
	v_exp_f32_e32 v38, v38
	v_exp_f32_e32 v39, v39
	v_mfma_f32_16x16x32_bf16 v[8:11], v[120:123], v[82:85], v[8:11]
	ds_read_b64 v[132:133], v77 offset:28672
	ds_read_b64 v[136:137], v77 offset:30720
	ds_read_b64 v[134:135], v78 offset:28672
	ds_read_b64 v[138:139], v78 offset:30720
	v_cvt_pk_bf16_f32 v90, v32, v33
	v_cvt_pk_bf16_f32 v91, v34, v35
	v_cvt_pk_bf16_f32 v92, v36, v37
	v_cvt_pk_bf16_f32 v93, v38, v39
	s_waitcnt lgkmcnt(0)
	s_nop 0
	v_mfma_f32_16x16x32_bf16 v[20:23], v[124:127], v[90:93], v[20:23]
	v_mfma_f32_16x16x32_bf16 v[8:11], v[128:131], v[90:93], v[8:11]
	ds_read_b64 v[140:141], v49 offset:28672
	ds_read_b64 v[160:161], v49 offset:30720
	ds_read_b64 v[142:143], v76 offset:28672
	ds_read_b64 v[162:163], v76 offset:30720
	s_andn2_b64 vcc, exec, s[30:31]
	v_mfma_f32_16x16x32_bf16 v[4:7], v[132:135], v[82:85], v[4:7]
	s_waitcnt lgkmcnt(0)
	v_mfma_f32_16x16x32_bf16 v[0:3], v[136:139], v[82:85], v[0:3]
	s_mov_b64 s[30:31], -1
	v_mfma_f32_16x16x32_bf16 v[4:7], v[140:143], v[90:93], v[4:7]
	v_mfma_f32_16x16x32_bf16 v[0:3], v[160:163], v[90:93], v[0:3]
	s_cbranch_vccnz .LBB0_107
	s_waitcnt vmcnt(0)
	s_mov_b64 s[30:31], 0

; template <bool SWA>
; DI void attn_phase(const Ctx& a, LAS unsigned char* lds) {
;     ...
;                 for (int jt = 0; jt < 4; ++jt) {
;                     const int row = 16 * jt + fr; const int sw = (row >> 1) & 7;
;                     const bf16x8 k0 = *(const LAS bf16x8*)(lds + AT_K + buf * 8192 + row * 128 + ((fq ^ sw) << 4));
;                     const bf16x8 k1 = *(const LAS bf16x8*)(lds + AT_K + buf * 8192 + row * 128 + (((4 + fq) ^ sw) << 4));
;                     f32x4 acc = (f32x4){0.f, 0.f, 0.f, 0.f}; acc = MFMA16(k0, qf[0], acc); acc = MFMA16(k1, qf[1], acc); sc[jt] = acc;
;                 }
;                 float sv[16]; bool ok[16];
; #pragma unroll
;                 for (int jt = 0; jt < 4; ++jt)
; #pragma unroll
;                     for (int rr = 0; rr < 4; ++rr) {
;                         bool valid = true;
;                         if (SWA && local) { const int dd = tkey0 + 16 * jt + 4 * fq + rr - (tq0 + fr); valid = (dd <= 128) && (dd >= -128); }
;                         sv[jt * 4 + rr] = valid ? sc[jt][rr] : -1e30f; ok[jt * 4 + rr] = valid;
;                     }
;                 float cmax = sv[0];
; #pragma unroll
;                 for (int e = 1; e < 16; ++e) cmax = fmaxf(cmax, sv[e]);
;                 cmax = fmaxf(cmax, shx(cmax, 16, lane)); cmax = fmaxf(cmax, shx(cmax, 32, lane));
;                 const float m_new = fmaxf(m_run, cmax);
;                 const float alpha = __builtin_amdgcn_exp2f((m_run - m_new) * LOG2E);
;                 float p[16], psum = 0.f;
; #pragma unroll
;                 for (int e = 0; e < 16; ++e) { p[e] = ok[e] ? __builtin_amdgcn_exp2f((sv[e] - m_new) * LOG2E) : 0.f; psum += p[e]; }
;                 l_run = l_run * alpha + psum; m_run = m_new;
;                 u32x4 pw0, pw1; pw0.x = pk2(p[0], p[1]); pw0.y = pk2(p[2], p[3]); pw0.z = pk2(p[4], p[5]); pw0.w = pk2(p[6], p[7]);
;                 pw1.x = pk2(p[8], p[9]); pw1.y = pk2(p[10], p[11]); pw1.z = pk2(p[12], p[13]); pw1.w = pk2(p[14], p[15]);
;                 const bf16x8 pf0 = __builtin_bit_cast(bf16x8, pw0), pf1 = __builtin_bit_cast(bf16x8, pw1);
;                 if (__builtin_amdgcn_ballot_w64(alpha != 1.f) != 0ull) {
; #pragma unroll
;                     for (int dt = 0; dt < 4; ++dt) o[dt] = o[dt] * alpha;
;                 }
;                 const int kc = (fq >> 1), kb8 = (fq & 1) * 8;
; #pragma unroll
.LBB0_144:
	ds_read_b128 v[8:11], v75
	ds_read_b128 v[12:15], v75 offset:2048
	ds_read_b128 v[16:19], v76
	ds_read_b128 v[20:23], v76 offset:2048
	s_mov_b32 s20, 0xf149f2ca
	s_waitcnt lgkmcnt(0)
	v_mfma_f32_16x16x32_bf16 v[8:11], v[8:11], v[0:3], 0
	v_mfma_f32_16x16x32_bf16 v[12:15], v[12:15], v[0:3], 0
	v_mfma_f32_16x16x32_bf16 v[8:11], v[16:19], v[4:7], v[8:11]
	ds_read_b128 v[16:19], v75 offset:4096
	v_mfma_f32_16x16x32_bf16 v[12:15], v[20:23], v[4:7], v[12:15]
	ds_read_b128 v[20:23], v76 offset:4096
	ds_read_b128 v[26:29], v75 offset:6144
	ds_read_b128 v[30:33], v76 offset:6144
	s_nop 2
	v_max_f32_e32 v25, v9, v9
	s_waitcnt lgkmcnt(0)
	v_mfma_f32_16x16x32_bf16 v[16:19], v[16:19], v[0:3], 0
	v_max_f32_e32 v34, v8, v8
	v_mfma_f32_16x16x32_bf16 v[16:19], v[20:23], v[4:7], v[16:19]
	v_max_f32_e32 v20, v34, v25
	v_max3_f32 v20, v20, v10, v11
	v_max3_f32 v25, v20, v12, v13
	v_mfma_f32_16x16x32_bf16 v[20:23], v[26:29], v[0:3], 0
	v_max3_f32 v25, v25, v14, v15
	s_nop 2
	v_max3_f32 v25, v25, v16, v17
	v_max3_f32 v25, v25, v18, v19
	v_mfma_f32_16x16x32_bf16 v[20:23], v[30:33], v[4:7], v[20:23]
	s_nop 7
	v_max3_f32 v25, v25, v20, v21
	v_max3_f32 v25, v25, v22, v23
	ds_bpermute_b32 v26, v69, v25
	s_waitcnt lgkmcnt(0)
	v_max_f32_e32 v26, v26, v26
	v_max_f32_e32 v25, v25, v26
	ds_bpermute_b32 v26, v70, v25
	s_waitcnt lgkmcnt(0)
	v_max3_f32 v58, v25, v26, s20
	v_sub_f32_e32 v8, v8, v58
	v_sub_f32_e32 v25, 0xf149f2ca, v58
	v_mul_f32_e32 v8, 0x3fb8aa3b, v8
	v_mul_f32_e32 v85, 0x3fb8aa3b, v25
	v_exp_f32_e32 v25, v8
	v_sub_f32_e32 v8, v11, v58
	v_mul_f32_e32 v8, 0x3fb8aa3b, v8
	v_exp_f32_e32 v28, v8
	v_sub_f32_e32 v8, v12, v58
	v_mul_f32_e32 v8, 0x3fb8aa3b, v8
	v_exp_f32_e32 v29, v8
	v_sub_f32_e32 v8, v13, v58
	v_mul_f32_e32 v8, 0x3fb8aa3b, v8
	v_exp_f32_e32 v30, v8
	v_sub_f32_e32 v8, v14, v58
	v_mul_f32_e32 v8, 0x3fb8aa3b, v8
	v_exp_f32_e32 v31, v8
	v_sub_f32_e32 v8, v15, v58
	v_mul_f32_e32 v8, 0x3fb8aa3b, v8
	v_exp_f32_e32 v32, v8
	v_sub_f32_e32 v8, v16, v58
	v_mul_f32_e32 v8, 0x3fb8aa3b, v8
	v_exp_f32_e32 v33, v8
	v_sub_f32_e32 v8, v17, v58
	v_mul_f32_e32 v8, 0x3fb8aa3b, v8
	v_exp_f32_e32 v34, v8
	v_sub_f32_e32 v8, v18, v58
	v_mul_f32_e32 v8, 0x3fb8aa3b, v8
	v_exp_f32_e32 v35, v8
	v_sub_f32_e32 v8, v19, v58
	v_mul_f32_e32 v8, 0x3fb8aa3b, v8
	v_exp_f32_e32 v36, v8
	v_sub_f32_e32 v8, v20, v58
	v_mul_f32_e32 v8, 0x3fb8aa3b, v8
	v_exp_f32_e32 v37, v8
	v_sub_f32_e32 v8, v21, v58
	v_mul_f32_e32 v8, 0x3fb8aa3b, v8
	v_exp_f32_e32 v38, v8
	v_sub_f32_e32 v8, v22, v58
	v_sub_f32_e32 v9, v9, v58
	v_mul_f32_e32 v8, 0x3fb8aa3b, v8
	ds_read_b64 v[116:117], v77 offset:24576
	ds_read_b64 v[124:125], v77 offset:26624
	v_mul_f32_e32 v9, 0x3fb8aa3b, v9
	v_exp_f32_e32 v39, v8
	v_exp_f32_e32 v8, v85
	v_exp_f32_e32 v26, v9
	v_sub_f32_e32 v9, v23, v58
	ds_read_b64 v[118:119], v78 offset:24576
	ds_read_b64 v[126:127], v78 offset:26624
	ds_read_b64 v[120:121], v79 offset:24576
	ds_read_b64 v[128:129], v79 offset:26624
	ds_read_b64 v[122:123], v80 offset:24576
	ds_read_b64 v[130:131], v80 offset:26624
	v_sub_f32_e32 v10, v10, v58
	v_mul_f32_e32 v10, 0x3fb8aa3b, v10
	v_mul_f32_e32 v9, 0x3fb8aa3b, v9
	v_exp_f32_e32 v27, v10
	v_exp_f32_e32 v85, v9
	v_mul_f32_e32 v86, 0, v8
	v_cmp_neq_f32_e32 vcc, 1.0, v8
	s_waitcnt lgkmcnt(0)
	s_cmp_lg_u64 vcc, 0
	s_cselect_b64 vcc, -1, 0
	v_cndmask_b32_e32 v92, 0, v86, vcc
	v_cvt_pk_bf16_f32 v12, v25, v26
	v_cvt_pk_bf16_f32 v13, v27, v28
	v_cvt_pk_bf16_f32 v14, v29, v30
	v_cvt_pk_bf16_f32 v15, v31, v32
	v_mov_b32_e32 v93, v92
	v_mov_b32_e32 v94, v92
	v_mov_b32_e32 v95, v92
	s_nop 1
	v_mfma_f32_16x16x32_bf16 v[8:11], v[116:119], v[12:15], v[92:95]
	v_cvt_pk_bf16_f32 v88, v33, v34
	v_cvt_pk_bf16_f32 v89, v35, v36
	v_cvt_pk_bf16_f32 v90, v37, v38
	v_cvt_pk_bf16_f32 v91, v39, v85
	s_nop 1
	v_mfma_f32_16x16x32_bf16 v[8:11], v[120:123], v[88:91], v[8:11]
	ds_read_b64 v[132:133], v77 offset:28672
	ds_read_b64 v[136:137], v77 offset:30720
	ds_read_b64 v[134:135], v78 offset:28672
	ds_read_b64 v[138:139], v78 offset:30720
	s_andn2_b64 vcc, exec, s[30:31]
	s_mov_b64 s[30:31], -1
	v_mfma_f32_16x16x32_bf16 v[16:19], v[124:127], v[12:15], v[92:95]
	v_mfma_f32_16x16x32_bf16 v[20:23], v[128:131], v[88:91], v[16:19]
	ds_read_b64 v[140:141], v79 offset:28672
	ds_read_b64 v[160:161], v79 offset:30720
	ds_read_b64 v[142:143], v80 offset:28672
	ds_read_b64 v[162:163], v80 offset:30720
	s_waitcnt lgkmcnt(0)
	s_nop 2
	v_mfma_f32_16x16x32_bf16 v[16:19], v[132:135], v[12:15], v[92:95]
	v_mfma_f32_16x16x32_bf16 v[12:15], v[136:139], v[12:15], v[92:95]
	v_mfma_f32_16x16x32_bf16 v[16:19], v[140:143], v[88:91], v[16:19]
	v_mfma_f32_16x16x32_bf16 v[12:15], v[160:163], v[88:91], v[12:15]
	s_cbranch_vccnz .LBB0_146
	s_waitcnt vmcnt(0)
	s_mov_b64 s[30:31], 0

; #define LAS __attribute__((address_space(3)))
; #define MFMA16(a, b, c) __builtin_amdgcn_mfma_f32_16x16x32_bf16((a), (b), (c), 0, 0, 0)
; template <bool SWA>
; DI void attn_phase(const Ctx& a, LAS unsigned char* lds) {
;     ...
;                 const int kc = (fq >> 1), kb8 = (fq & 1) * 8;
; #pragma unroll
;                 for (int dt = 0; dt < 4; ++dt) {
;                     const int d = 16 * dt + fr, sw = (d >> 1) & 7; const int vb = AT_V + buf * 8192 + d * 128 + kb8;
;                     const s16x4 v0 = *(const LAS s16x4*)(lds + vb + ((kc ^ sw) << 4)), v1 = *(const LAS s16x4*)(lds + vb + (((kc + 2) ^ sw) << 4));
;                     const s16x4 v2 = *(const LAS s16x4*)(lds + vb + (((kc + 4) ^ sw) << 4)), v3 = *(const LAS s16x4*)(lds + vb + (((kc + 6) ^ sw) << 4));
;                     o[dt] = MFMA16(__builtin_shufflevector(v0, v1, 0, 1, 2, 3, 4, 5, 6, 7), pf0, o[dt]);
;                     o[dt] = MFMA16(__builtin_shufflevector(v2, v3, 0, 1, 2, 3, 4, 5, 6, 7), pf1, o[dt]);
;                 }
.LBB0_153:
	ds_read_b64 v[116:117], v77 offset:32768
	ds_read_b64 v[120:121], v77 offset:34816
	s_mov_b32 s98, 0x3fb8aa3b
	v_mul_f32_e32 v190, 0xbfb8aa3b, v87
	v_fma_f32 v24, v24, s98, v190
	v_fma_f32 v25, v25, s98, v190
	v_fma_f32 v26, v26, s98, v190
	v_fma_f32 v27, v27, s98, v190
	v_fma_f32 v28, v28, s98, v190
	v_fma_f32 v29, v29, s98, v190
	v_fma_f32 v30, v30, s98, v190
	v_fma_f32 v31, v31, s98, v190
	v_exp_f32_e32 v24, v24
	v_exp_f32_e32 v25, v25
	v_exp_f32_e32 v26, v26
	v_exp_f32_e32 v27, v27
	v_exp_f32_e32 v28, v28
	v_exp_f32_e32 v29, v29
	v_exp_f32_e32 v30, v30
	v_exp_f32_e32 v31, v31
	s_waitcnt lgkmcnt(0)
	ds_read_b64 v[118:119], v78 offset:32768
	ds_read_b64 v[122:123], v78 offset:34816
	ds_read_b64 v[124:125], v79 offset:32768
	ds_read_b64 v[128:129], v79 offset:34816
	ds_read_b64 v[126:127], v80 offset:32768
	ds_read_b64 v[130:131], v80 offset:34816
	v_cvt_pk_bf16_f32 v88, v24, v25
	v_cvt_pk_bf16_f32 v89, v26, v27
	v_cvt_pk_bf16_f32 v90, v28, v29
	v_cvt_pk_bf16_f32 v91, v30, v31
	v_fma_f32 v32, v32, s98, v190
	v_fma_f32 v33, v33, s98, v190
	s_waitcnt lgkmcnt(0)
	v_mfma_f32_16x16x32_bf16 v[8:11], v[116:119], v[88:91], v[8:11]
	v_fma_f32 v34, v34, s98, v190
	v_fma_f32 v35, v35, s98, v190
	v_fma_f32 v36, v36, s98, v190
	v_fma_f32 v37, v37, s98, v190
	v_fma_f32 v38, v38, s98, v190
	v_fma_f32 v39, v39, s98, v190
	v_exp_f32_e32 v32, v32
	v_exp_f32_e32 v33, v33
	v_exp_f32_e32 v34, v34
	v_exp_f32_e32 v35, v35
	v_exp_f32_e32 v36, v36
	v_exp_f32_e32 v37, v37
	v_exp_f32_e32 v38, v38
	v_exp_f32_e32 v39, v39
	v_mfma_f32_16x16x32_bf16 v[20:23], v[120:123], v[88:91], v[20:23]
	ds_read_b64 v[132:133], v77 offset:36864
	ds_read_b64 v[136:137], v77 offset:38912
	ds_read_b64 v[134:135], v78 offset:36864
	ds_read_b64 v[138:139], v78 offset:38912
	v_cvt_pk_bf16_f32 v96, v32, v33
	v_cvt_pk_bf16_f32 v97, v34, v35
	v_cvt_pk_bf16_f32 v98, v36, v37
	v_cvt_pk_bf16_f32 v99, v38, v39
	s_waitcnt lgkmcnt(0)
	s_nop 0
	v_mfma_f32_16x16x32_bf16 v[8:11], v[124:127], v[96:99], v[8:11]
	v_mfma_f32_16x16x32_bf16 v[20:23], v[128:131], v[96:99], v[20:23]
	ds_read_b64 v[140:141], v79 offset:36864
	ds_read_b64 v[160:161], v79 offset:38912
	ds_read_b64 v[142:143], v80 offset:36864
	ds_read_b64 v[162:163], v80 offset:38912
	s_andn2_b64 vcc, exec, s[30:31]
	v_mfma_f32_16x16x32_bf16 v[16:19], v[132:135], v[88:91], v[16:19]
	s_waitcnt lgkmcnt(0)
	v_mfma_f32_16x16x32_bf16 v[12:15], v[136:139], v[88:91], v[12:15]
	s_mov_b64 s[30:31], -1
	v_mfma_f32_16x16x32_bf16 v[16:19], v[140:143], v[96:99], v[16:19]
	v_mfma_f32_16x16x32_bf16 v[12:15], v[160:163], v[96:99], v[12:15]
	s_cbranch_vccnz .LBB0_155
	s_waitcnt vmcnt(0)
	s_mov_b64 s[30:31], 0

; #define LAS __attribute__((address_space(3)))
; #define MFMA16(a, b, c) __builtin_amdgcn_mfma_f32_16x16x32_bf16((a), (b), (c), 0, 0, 0)
; template <bool SWA>
; DI void attn_phase(const Ctx& a, LAS unsigned char* lds) {
;     ...
;                 const int kc = (fq >> 1), kb8 = (fq & 1) * 8;
; #pragma unroll
;                 for (int dt = 0; dt < 4; ++dt) {
;                     const int d = 16 * dt + fr, sw = (d >> 1) & 7; const int vb = AT_V + buf * 8192 + d * 128 + kb8;
;                     const s16x4 v0 = *(const LAS s16x4*)(lds + vb + ((kc ^ sw) << 4)), v1 = *(const LAS s16x4*)(lds + vb + (((kc + 2) ^ sw) << 4));
;                     const s16x4 v2 = *(const LAS s16x4*)(lds + vb + (((kc + 4) ^ sw) << 4)), v3 = *(const LAS s16x4*)(lds + vb + (((kc + 6) ^ sw) << 4));
;                     o[dt] = MFMA16(__builtin_shufflevector(v0, v1, 0, 1, 2, 3, 4, 5, 6, 7), pf0, o[dt]);
;                     o[dt] = MFMA16(__builtin_shufflevector(v2, v3, 0, 1, 2, 3, 4, 5, 6, 7), pf1, o[dt]);
;                 }
.LBB0_162:
	ds_read_b64 v[116:117], v77 offset:40960
	ds_read_b64 v[120:121], v77 offset:43008
	s_mov_b32 s98, 0x3fb8aa3b
	v_mul_f32_e32 v190, 0xbfb8aa3b, v85
	v_fma_f32 v24, v24, s98, v190
	v_fma_f32 v25, v25, s98, v190
	v_fma_f32 v26, v26, s98, v190
	v_fma_f32 v27, v27, s98, v190
	v_fma_f32 v28, v28, s98, v190
	v_fma_f32 v29, v29, s98, v190
	v_fma_f32 v30, v30, s98, v190
	v_fma_f32 v31, v31, s98, v190
	v_exp_f32_e32 v24, v24
	v_exp_f32_e32 v25, v25
	v_exp_f32_e32 v26, v26
	v_exp_f32_e32 v27, v27
	v_exp_f32_e32 v28, v28
	v_exp_f32_e32 v29, v29
	v_exp_f32_e32 v30, v30
	v_exp_f32_e32 v31, v31
	s_waitcnt lgkmcnt(0)
	ds_read_b64 v[118:119], v78 offset:40960
	ds_read_b64 v[122:123], v78 offset:43008
	ds_read_b64 v[124:125], v79 offset:40960
	ds_read_b64 v[128:129], v79 offset:43008
	ds_read_b64 v[126:127], v80 offset:40960
	ds_read_b64 v[130:131], v80 offset:43008
	v_cvt_pk_bf16_f32 v88, v24, v25
	v_cvt_pk_bf16_f32 v89, v26, v27
	v_cvt_pk_bf16_f32 v90, v28, v29
	v_cvt_pk_bf16_f32 v91, v30, v31
	v_fma_f32 v32, v32, s98, v190
	v_fma_f32 v33, v33, s98, v190
	s_waitcnt lgkmcnt(0)
	v_mfma_f32_16x16x32_bf16 v[8:11], v[116:119], v[88:91], v[8:11]
	v_fma_f32 v34, v34, s98, v190
	v_fma_f32 v35, v35, s98, v190
	v_fma_f32 v36, v36, s98, v190
	v_fma_f32 v37, v37, s98, v190
	v_fma_f32 v38, v38, s98, v190
	v_fma_f32 v39, v39, s98, v190
	v_exp_f32_e32 v32, v32
	v_exp_f32_e32 v33, v33
	v_exp_f32_e32 v34, v34
	v_exp_f32_e32 v35, v35
	v_exp_f32_e32 v36, v36
	v_exp_f32_e32 v37, v37
	v_exp_f32_e32 v38, v38
	v_exp_f32_e32 v39, v39
	v_mfma_f32_16x16x32_bf16 v[20:23], v[120:123], v[88:91], v[20:23]
	ds_read_b64 v[132:133], v77 offset:45056
	ds_read_b64 v[136:137], v77 offset:47104
	ds_read_b64 v[134:135], v78 offset:45056
	ds_read_b64 v[138:139], v78 offset:47104
	v_cvt_pk_bf16_f32 v96, v32, v33
	v_cvt_pk_bf16_f32 v97, v34, v35
	v_cvt_pk_bf16_f32 v98, v36, v37
	v_cvt_pk_bf16_f32 v99, v38, v39
	s_waitcnt lgkmcnt(0)
	s_nop 0
	v_mfma_f32_16x16x32_bf16 v[8:11], v[124:127], v[96:99], v[8:11]
	v_mfma_f32_16x16x32_bf16 v[20:23], v[128:131], v[96:99], v[20:23]
	ds_read_b64 v[140:141], v79 offset:45056
	ds_read_b64 v[160:161], v79 offset:47104
	ds_read_b64 v[142:143], v80 offset:45056
	ds_read_b64 v[162:163], v80 offset:47104
	s_andn2_b64 vcc, exec, s[30:31]
	v_mfma_f32_16x16x32_bf16 v[16:19], v[132:135], v[88:91], v[16:19]
	s_waitcnt lgkmcnt(0)
	v_mfma_f32_16x16x32_bf16 v[12:15], v[136:139], v[88:91], v[12:15]
	s_mov_b64 s[30:31], -1
	v_mfma_f32_16x16x32_bf16 v[16:19], v[140:143], v[96:99], v[16:19]
	v_mfma_f32_16x16x32_bf16 v[12:15], v[160:163], v[96:99], v[12:15]
	s_cbranch_vccnz .LBB0_164
	s_waitcnt vmcnt(0)
	s_mov_b64 s[30:31], 0

; #define LAS __attribute__((address_space(3)))
; #define MFMA16(a, b, c) __builtin_amdgcn_mfma_f32_16x16x32_bf16((a), (b), (c), 0, 0, 0)
; template <bool SWA>
; DI void attn_phase(const Ctx& a, LAS unsigned char* lds) {
;     ...
;                 const int kc = (fq >> 1), kb8 = (fq & 1) * 8;
; #pragma unroll
;                 for (int dt = 0; dt < 4; ++dt) {
;                     const int d = 16 * dt + fr, sw = (d >> 1) & 7; const int vb = AT_V + buf * 8192 + d * 128 + kb8;
;                     const s16x4 v0 = *(const LAS s16x4*)(lds + vb + ((kc ^ sw) << 4)), v1 = *(const LAS s16x4*)(lds + vb + (((kc + 2) ^ sw) << 4));
;                     const s16x4 v2 = *(const LAS s16x4*)(lds + vb + (((kc + 4) ^ sw) << 4)), v3 = *(const LAS s16x4*)(lds + vb + (((kc + 6) ^ sw) << 4));
;                     o[dt] = MFMA16(__builtin_shufflevector(v0, v1, 0, 1, 2, 3, 4, 5, 6, 7), pf0, o[dt]);
;                     o[dt] = MFMA16(__builtin_shufflevector(v2, v3, 0, 1, 2, 3, 4, 5, 6, 7), pf1, o[dt]);
;                 }
.LBB0_171:
	ds_read_b64 v[116:117], v77 offset:24576
	ds_read_b64 v[120:121], v77 offset:26624
	s_mov_b32 s98, 0x3fb8aa3b
	v_mul_f32_e32 v190, 0xbfb8aa3b, v49
	v_fma_f32 v24, v24, s98, v190
	v_fma_f32 v25, v25, s98, v190
	v_fma_f32 v26, v26, s98, v190
	v_fma_f32 v27, v27, s98, v190
	v_fma_f32 v28, v28, s98, v190
	v_fma_f32 v29, v29, s98, v190
	v_fma_f32 v30, v30, s98, v190
	v_fma_f32 v31, v31, s98, v190
	v_exp_f32_e32 v24, v24
	v_exp_f32_e32 v25, v25
	v_exp_f32_e32 v26, v26
	v_exp_f32_e32 v27, v27
	v_exp_f32_e32 v28, v28
	v_exp_f32_e32 v29, v29
	v_exp_f32_e32 v30, v30
	v_exp_f32_e32 v31, v31
	s_waitcnt lgkmcnt(0)
	ds_read_b64 v[118:119], v78 offset:24576
	ds_read_b64 v[122:123], v78 offset:26624
	ds_read_b64 v[124:125], v79 offset:24576
	ds_read_b64 v[128:129], v79 offset:26624
	ds_read_b64 v[126:127], v80 offset:24576
	ds_read_b64 v[130:131], v80 offset:26624
	v_cvt_pk_bf16_f32 v86, v24, v25
	v_cvt_pk_bf16_f32 v87, v26, v27
	v_cvt_pk_bf16_f32 v88, v28, v29
	v_cvt_pk_bf16_f32 v89, v30, v31
	v_fma_f32 v32, v32, s98, v190
	v_fma_f32 v33, v33, s98, v190
	s_waitcnt lgkmcnt(0)
	v_mfma_f32_16x16x32_bf16 v[8:11], v[116:119], v[86:89], v[8:11]
	v_fma_f32 v34, v34, s98, v190
	v_fma_f32 v35, v35, s98, v190
	v_fma_f32 v36, v36, s98, v190
	v_fma_f32 v37, v37, s98, v190
	v_fma_f32 v38, v38, s98, v190
	v_fma_f32 v39, v39, s98, v190
	v_exp_f32_e32 v32, v32
	v_exp_f32_e32 v33, v33
	v_exp_f32_e32 v34, v34
	v_exp_f32_e32 v35, v35
	v_exp_f32_e32 v36, v36
	v_exp_f32_e32 v37, v37
	v_exp_f32_e32 v38, v38
	v_exp_f32_e32 v39, v39
	v_mfma_f32_16x16x32_bf16 v[20:23], v[120:123], v[86:89], v[20:23]
	ds_read_b64 v[132:133], v77 offset:28672
	ds_read_b64 v[136:137], v77 offset:30720
	ds_read_b64 v[134:135], v78 offset:28672
	ds_read_b64 v[138:139], v78 offset:30720
	v_cvt_pk_bf16_f32 v94, v32, v33
	v_cvt_pk_bf16_f32 v95, v34, v35
	v_cvt_pk_bf16_f32 v96, v36, v37
	v_cvt_pk_bf16_f32 v97, v38, v39
	s_waitcnt lgkmcnt(0)
	s_nop 0
	v_mfma_f32_16x16x32_bf16 v[8:11], v[124:127], v[94:97], v[8:11]
	v_mfma_f32_16x16x32_bf16 v[20:23], v[128:131], v[94:97], v[20:23]
	ds_read_b64 v[140:141], v79 offset:28672
	ds_read_b64 v[160:161], v79 offset:30720
	ds_read_b64 v[142:143], v80 offset:28672
	ds_read_b64 v[162:163], v80 offset:30720
	s_andn2_b64 vcc, exec, s[30:31]
	v_mfma_f32_16x16x32_bf16 v[16:19], v[132:135], v[86:89], v[16:19]
	s_waitcnt lgkmcnt(0)
	v_mfma_f32_16x16x32_bf16 v[12:15], v[136:139], v[86:89], v[12:15]
	s_mov_b64 s[30:31], -1
	v_mfma_f32_16x16x32_bf16 v[16:19], v[140:143], v[94:97], v[16:19]
	v_mfma_f32_16x16x32_bf16 v[12:15], v[160:163], v[94:97], v[12:15]
	s_cbranch_vccnz .LBB0_173
	s_waitcnt vmcnt(0)
	s_mov_b64 s[30:31], 0
